# sc8 + static s_setprio 1 for waves 4-7 (younger half) during P5, reset at P6 entry
# speedup vs baseline: 1.0062x; 1.0062x over previous
.LBB0_863:
	s_or_b64 exec, exec, s[4:5]
	s_ashr_i32 s4, s24, 8
	s_cmp_eq_u32 s4, 1
	s_waitcnt vmcnt(0)
	v_lshl_add_u64 v[136:137], s[18:19], 0, v[228:229]
	v_lshl_add_u64 v[134:135], s[18:19], 0, v[232:233]
	v_lshl_add_u64 v[130:131], s[16:17], 0, v[226:227]
	s_cselect_b64 s[2:3], -1, 0
	s_cmp_lg_u32 s4, 1
	v_lshl_add_u64 v[132:133], s[16:17], 0, v[230:231]
	s_cbranch_scc1 .LBB0_865
	s_setprio 1
	s_barrier

.LBB0_959:
	s_setprio 0
	s_cmp_lt_i32 s44, 7
	s_cselect_b64 s[2:3], -1, 0
	s_cmp_gt_i32 s45, 6
	s_cselect_b64 s[4:5], -1, 0
	s_and_b64 s[2:3], s[2:3], s[4:5]
	s_andn2_b64 vcc, exec, s[2:3]
	s_cbranch_vccnz .LBB0_964
	s_add_u32 s33, s42, 0xe800000
	s_addc_u32 s39, s43, 0
	s_add_u32 s41, s42, 0x1200000
	s_addc_u32 s48, s43, 0
	s_add_i32 s2, 0, 0x23158
	v_mov_b32_e32 v1, s2
	s_waitcnt lgkmcnt(0)
	ds_read_b64 v[2:3], v1
	s_cmpk_lt_i32 s40, 0x200
	s_movk_i32 s7, 0xb00
	v_readfirstlane_b32 s6, v0
	s_waitcnt lgkmcnt(0)
	v_readfirstlane_b32 s8, v2
	v_readfirstlane_b32 s9, v3
	s_cselect_b64 s[2:3], -1, 0
	s_cmpk_gt_i32 s40, 0x1ff
	s_cbranch_scc1 .LBB0_963
	s_ashr_i32 s4, s40, 31
	s_lshr_b32 s4, s4, 29
	s_add_i32 s12, s40, s4
	s_and_b32 s4, s12, -8
	s_sub_i32 s10, s40, s4
	s_cmp_gt_i32 s10, -1
	s_cbranch_scc0 .LBB0_965
	s_lshl_b32 s11, s10, 6
	s_ashr_i32 s4, s12, 3
	s_cbranch_execz .LBB0_966
	s_branch .LBB0_967
